# post phase: neighbour-row and gate loads issued at top of iteration, loop-invariant params hoisted out of loop
# speedup vs baseline: 1.1112x; 1.0069x over previous
.LBB0_278:
	s_andn2_b64 vcc, exec, s[2:3]
	s_cbranch_vccnz .LBB0_700
	s_lshl_b64 s[2:3], s[28:29], 9
	s_mul_hi_i32 s63, s28, 0x780
	s_mul_i32 s62, s28, 0x780
	s_cmp_lt_i32 s94, 3
	s_mov_b64 s[22:23], -1
	s_cbranch_scc1 .LBB0_497
	s_cmp_lt_i32 s94, 4
	s_cbranch_scc1 .LBB0_371
	s_cmp_gt_i32 s94, 4
	s_cbranch_scc0 .LBB0_298
	s_mov_b64 s[38:39], s[96:97]
	v_mov_b32_e32 v2, v1
	v_readlane_b32 s22, v245, 2
	v_ashrrev_i32_e32 v3, 6, v2
	s_nop 0
	v_add_u32_e32 v48, s22, v3
	s_mov_b32 s22, 0x8000
	v_cmp_gt_i32_e32 vcc, s22, v48
	s_and_saveexec_b64 s[22:23], vcc
	s_cbranch_execz .LBB0_297
	s_load_dwordx2 s[44:45], s[38:39], 0xf8
	s_load_dwordx2 s[46:47], s[38:39], 0xa0
	s_load_dwordx4 s[40:43], s[38:39], 0x90
	v_lshlrev_b32_e32 v2, 3, v2
	v_and_b32_e32 v2, 0x1f8, v2
	v_lshlrev_b32_e32 v4, 2, v2
	s_waitcnt lgkmcnt(0)
	s_add_u32 s30, s44, 0x6400000
	s_addc_u32 s31, s45, 0
	s_lshl_b64 s[48:49], s[2:3], 2
	s_add_u32 s42, s42, s48
	s_addc_u32 s43, s43, s49
	v_mov_b32_e32 v5, v34
	v_lshl_add_u64 v[50:51], s[42:43], 0, v[4:5]
	s_add_u32 s42, s46, s48
	s_addc_u32 s43, s47, s49
	s_add_u32 s40, s40, s48
	s_addc_u32 s41, s41, s49
	v_lshlrev_b32_e32 v6, 1, v2
	v_mov_b32_e32 v7, v34
	v_lshl_add_u64 v[54:55], s[40:41], 0, v[4:5]
	v_lshl_add_u64 v[6:7], s[44:45], 0, v[6:7]
	s_mov_b64 s[40:41], 0x1dc00000
	v_lshl_add_u64 v[52:53], s[42:43], 0, v[4:5]
	v_lshl_add_u64 v[56:57], v[6:7], 0, s[40:41]
	s_load_dwordx4 s[40:43], s[38:39], 0x48
	s_load_dword s24, s[72:73], 0x10
	s_lshl_b64 s[38:39], s[62:63], 2
	v_cmp_lt_i32_e32 vcc, v219, v218
	v_or_b32_e32 v6, 0x800, v2
	s_waitcnt lgkmcnt(0)
	s_add_u32 s42, s42, s38
	s_addc_u32 s43, s43, s39
	s_add_u32 s38, s40, s38
	s_addc_u32 s39, s41, s39
	s_lshr_b32 s24, s24, 16
	s_cmp_lg_u32 s24, 0
	v_cndmask_b32_e32 v3, v217, v219, vcc
	v_cmp_lt_i32_e32 vcc, v220, v218
	s_cselect_b64 s[40:41], -1, 0
	v_lshlrev_b32_e32 v35, 2, v3
	v_cndmask_b32_e32 v3, v217, v220, vcc
	v_cmp_lt_i32_e32 vcc, v221, v218
	s_cmp_lg_u64 s[40:41], 0
	v_lshlrev_b32_e32 v63, 2, v3
	v_cndmask_b32_e32 v3, v217, v221, vcc
	s_addc_u32 s24, s74, 0
	v_lshl_add_u64 v[58:59], s[38:39], 0, v[4:5]
	v_lshl_add_u64 v[60:61], s[42:43], 0, v[4:5]
	v_or_b32_e32 v4, 0x1000, v4
	v_lshlrev_b32_e32 v65, 2, v3
	s_lshl_b32 s24, s24, 3
	v_or_b32_e32 v62, 0xa00, v2
	v_or_b32_e32 v64, 0xc00, v2
	v_lshl_add_u64 v[66:67], s[38:39], 0, v[4:5]
	v_lshl_add_u64 v[68:69], s[42:43], 0, v[4:5]
	s_mov_b64 s[40:41], 0
	v_lshlrev_b32_e32 v70, 1, v2
	v_lshlrev_b32_e32 v72, 1, v6
	global_load_dwordx4 v[178:181], v[54:55], off offset:16
	global_load_dwordx4 v[182:185], v[54:55], off
	global_load_dwordx4 v[186:189], v[66:67], off offset:16
	global_load_dwordx4 v[190:193], v[66:67], off
	global_load_dwordx4 v[194:197], v[68:69], off offset:16
	global_load_dwordx4 v[198:201], v[68:69], off
	global_load_dwordx4 v[202:205], v[50:51], off offset:16
	global_load_dwordx4 v[206:209], v[50:51], off
	global_load_dwordx4 v[226:229], v[52:53], off offset:16
	global_load_dwordx4 v[230:233], v[52:53], off
	s_waitcnt vmcnt(0)
	s_branch .LBB0_285
.LBB0_284:
	s_or_b64 exec, exec, s[42:43]
	s_waitcnt vmcnt(5)
	v_cvt_f32_f16_sdwa v117, v22 dst_sel:DWORD dst_unused:UNUSED_PAD src0_sel:WORD_1
	v_cvt_f32_f16_e32 v116, v22
	v_cvt_f32_f16_sdwa v135, v23 dst_sel:DWORD dst_unused:UNUSED_PAD src0_sel:WORD_1
	v_cvt_f32_f16_e32 v134, v23
	v_cvt_f32_f16_sdwa v23, v24 dst_sel:DWORD dst_unused:UNUSED_PAD src0_sel:WORD_1
	v_cvt_f32_f16_e32 v22, v24
	v_cvt_f32_f16_sdwa v139, v25 dst_sel:DWORD dst_unused:UNUSED_PAD src0_sel:WORD_1
	v_cvt_f32_f16_e32 v138, v25
	v_pk_add_f32 v[24:25], v[126:127], v[116:117] neg_lo:[0,1] neg_hi:[0,1]
	v_ashrrev_i32_e32 v49, 31, v48
	s_waitcnt vmcnt(3)
	v_pk_fma_f32 v[24:25], v[24:25], v[44:45], v[116:117]
	v_pk_add_f32 v[44:45], v[132:133], v[116:117] neg_lo:[0,1] neg_hi:[0,1]
	s_waitcnt vmcnt(1)
	v_pk_fma_f32 v[44:45], v[44:45], v[40:41], v[24:25]
	v_pk_add_f32 v[24:25], v[124:125], v[134:135] neg_lo:[0,1] neg_hi:[0,1]
	v_pk_add_f32 v[40:41], v[130:131], v[134:135] neg_lo:[0,1] neg_hi:[0,1]
	v_pk_fma_f32 v[24:25], v[24:25], v[46:47], v[134:135]
	s_nop 0
	v_pk_fma_f32 v[24:25], v[40:41], v[42:43], v[24:25]
	v_pk_add_f32 v[40:41], v[122:123], v[22:23] neg_lo:[0,1] neg_hi:[0,1]
	v_cvt_f32_f16_sdwa v43, v5 dst_sel:DWORD dst_unused:UNUSED_PAD src0_sel:WORD_1
	v_pk_fma_f32 v[30:31], v[40:41], v[30:31], v[22:23]
	v_pk_add_f32 v[22:23], v[128:129], v[22:23] neg_lo:[0,1] neg_hi:[0,1]
	s_waitcnt vmcnt(0)
	v_cvt_f32_f16_sdwa v41, v27 dst_sel:DWORD dst_unused:UNUSED_PAD src0_sel:WORD_1
	v_pk_fma_f32 v[30:31], v[22:23], v[36:37], v[30:31]
	v_pk_add_f32 v[22:23], v[120:121], v[138:139] neg_lo:[0,1] neg_hi:[0,1]
	v_cvt_f32_f16_e32 v40, v27
	v_pk_fma_f32 v[22:23], v[22:23], v[32:33], v[138:139]
	v_pk_add_f32 v[32:33], v[118:119], v[138:139] neg_lo:[0,1] neg_hi:[0,1]
	v_cvt_f32_f16_sdwa v27, v2 dst_sel:DWORD dst_unused:UNUSED_PAD src0_sel:WORD_1
	v_pk_fma_f32 v[32:33], v[32:33], v[38:39], v[22:23]
	v_cvt_f32_f16_sdwa v23, v26 dst_sel:DWORD dst_unused:UNUSED_PAD src0_sel:WORD_1
	v_cvt_f32_f16_e32 v22, v26
	v_cvt_f32_f16_e32 v26, v2
	v_cvt_f32_f16_sdwa v39, v28 dst_sel:DWORD dst_unused:UNUSED_PAD src0_sel:WORD_1
	v_cvt_f32_f16_e32 v38, v28
	v_cvt_f32_f16_sdwa v37, v29 dst_sel:DWORD dst_unused:UNUSED_PAD src0_sel:WORD_1
	v_cvt_f32_f16_e32 v36, v29
	v_cvt_f32_f16_sdwa v29, v3 dst_sel:DWORD dst_unused:UNUSED_PAD src0_sel:WORD_1
	v_cvt_f32_f16_e32 v28, v3
	v_cvt_f32_f16_sdwa v3, v4 dst_sel:DWORD dst_unused:UNUSED_PAD src0_sel:WORD_1
	v_cvt_f32_f16_e32 v2, v4
	v_cvt_f32_f16_e32 v42, v5
	v_pk_add_f32 v[4:5], v[104:105], v[26:27] neg_lo:[0,1] neg_hi:[0,1]
	s_nop 0
	v_pk_fma_f32 v[4:5], v[4:5], v[18:19], v[26:27]
	v_pk_add_f32 v[18:19], v[114:115], v[26:27] neg_lo:[0,1] neg_hi:[0,1]
	s_nop 0
	v_pk_fma_f32 v[4:5], v[18:19], v[14:15], v[4:5]
	v_pk_add_f32 v[14:15], v[108:109], v[28:29] neg_lo:[0,1] neg_hi:[0,1]
	v_pk_add_f32 v[18:19], v[112:113], v[28:29] neg_lo:[0,1] neg_hi:[0,1]
	v_pk_fma_f32 v[14:15], v[14:15], v[20:21], v[28:29]
	s_nop 0
	v_pk_fma_f32 v[14:15], v[18:19], v[16:17], v[14:15]
	v_pk_add_f32 v[16:17], v[106:107], v[2:3] neg_lo:[0,1] neg_hi:[0,1]
	s_nop 0
	v_pk_fma_f32 v[6:7], v[16:17], v[6:7], v[2:3]
	v_pk_add_f32 v[2:3], v[110:111], v[2:3] neg_lo:[0,1] neg_hi:[0,1]
	s_nop 0
	v_pk_fma_f32 v[6:7], v[2:3], v[10:11], v[6:7]
	v_pk_add_f32 v[2:3], v[102:103], v[42:43] neg_lo:[0,1] neg_hi:[0,1]
	v_pk_mul_f32 v[10:11], v[4:5], v[44:45]
	v_pk_fma_f32 v[2:3], v[2:3], v[8:9], v[42:43]
	v_pk_add_f32 v[8:9], v[96:97], v[42:43] neg_lo:[0,1] neg_hi:[0,1]
	v_pk_mul_f32 v[6:7], v[6:7], v[30:31]
	v_pk_fma_f32 v[8:9], v[8:9], v[12:13], v[2:3]
	s_waitcnt lgkmcnt(0)
	v_add_f32_e32 v2, v71, v136
	v_fmamk_f32 v2, v2, 0x3c800000, v213
	v_cmp_gt_f32_e32 vcc, s27, v2
	v_mul_f32_e32 v3, 0x4b800000, v2
	s_nop 0
	v_cndmask_b32_e32 v2, v2, v3, vcc
	v_rsq_f32_e32 v12, v2
	v_mov_b32_e32 v2, v178
	v_mov_b32_e32 v3, v179
	v_mov_b32_e32 v4, v180
	v_mov_b32_e32 v5, v181
	v_mov_b32_e32 v16, v182
	v_mov_b32_e32 v17, v183
	v_mov_b32_e32 v18, v184
	v_mov_b32_e32 v19, v185
	v_mul_f32_e32 v13, 0x45800000, v12
	v_cndmask_b32_e32 v42, v12, v13, vcc
	v_pk_mul_f32 v[82:83], v[82:83], v[42:43] op_sel_hi:[1,0]
	s_waitcnt vmcnt(1)
	v_pk_mul_f32 v[2:3], v[6:7], v[2:3]
	s_waitcnt vmcnt(0)
	v_pk_mul_f32 v[10:11], v[10:11], v[16:17]
	s_nop 0
	v_add_f32_e32 v10, 0, v10
	v_add_f32_e32 v16, v10, v11
	v_pk_mul_f32 v[10:11], v[14:15], v[24:25]
	s_nop 0
	v_pk_mul_f32 v[10:11], v[10:11], v[18:19]
	s_nop 0
	v_add_f32_e32 v10, v16, v10
	v_add_f32_e32 v10, v10, v11
	v_add_f32_e32 v2, v10, v2
	v_add_f32_e32 v6, v2, v3
	v_pk_mul_f32 v[2:3], v[8:9], v[32:33]
	v_pk_add_f32 v[10:11], v[98:99], v[22:23] neg_lo:[0,1] neg_hi:[0,1]
	v_pk_mul_f32 v[2:3], v[2:3], v[4:5]
	s_nop 0
	v_add_f32_e32 v2, v6, v2
	v_add_f32_e32 v2, v2, v3
	ds_bpermute_b32 v3, v35, v2
	s_waitcnt lgkmcnt(0)
	v_add_f32_e32 v2, v2, v3
	ds_bpermute_b32 v3, v63, v2
	s_waitcnt lgkmcnt(0)
	v_add_f32_e32 v2, v2, v3
	ds_bpermute_b32 v3, v65, v2
	s_waitcnt lgkmcnt(0)
	v_add_f32_e32 v44, v2, v3
	v_lshlrev_b64 v[2:3], 10, v[48:49]
	v_lshl_add_u64 v[2:3], v[56:57], 0, v[2:3]
	v_mov_b32_e32 v2, v174
	v_mov_b32_e32 v3, v175
	v_mov_b32_e32 v4, v176
	v_mov_b32_e32 v5, v177
	s_nop 0
	v_mov_b32_e32 v6, v186
	v_mov_b32_e32 v7, v187
	v_mov_b32_e32 v8, v188
	v_mov_b32_e32 v9, v189
	v_mov_b32_e32 v12, v190
	v_mov_b32_e32 v13, v191
	v_mov_b32_e32 v14, v192
	v_mov_b32_e32 v15, v193
	v_add_u32_e32 v48, s24, v48
	v_cmp_lt_i32_e32 vcc, s75, v48
	s_or_b64 s[40:41], vcc, s[40:41]
	s_waitcnt vmcnt(2)
	v_cvt_f32_f16_e32 v96, v2
	v_cvt_f32_f16_sdwa v97, v2 dst_sel:DWORD dst_unused:UNUSED_PAD src0_sel:WORD_1
	s_waitcnt vmcnt(0)
	v_pk_fma_f32 v[16:17], v[10:11], v[12:13], v[22:23]
	v_mov_b32_e32 v10, v194
	v_mov_b32_e32 v11, v195
	v_mov_b32_e32 v12, v196
	v_mov_b32_e32 v13, v197
	v_mov_b32_e32 v18, v198
	v_mov_b32_e32 v19, v199
	v_mov_b32_e32 v20, v200
	v_mov_b32_e32 v21, v201
	v_pk_add_f32 v[22:23], v[100:101], v[22:23] neg_lo:[0,1] neg_hi:[0,1]
	v_cvt_f32_f16_e32 v2, v3
	v_cvt_f32_f16_sdwa v3, v3 dst_sel:DWORD dst_unused:UNUSED_PAD src0_sel:WORD_1
	s_waitcnt vmcnt(0)
	v_pk_fma_f32 v[46:47], v[22:23], v[18:19], v[16:17]
	v_mov_b32_e32 v16, v202
	v_mov_b32_e32 v17, v203
	v_mov_b32_e32 v18, v204
	v_mov_b32_e32 v19, v205
	v_mov_b32_e32 v26, v206
	v_mov_b32_e32 v27, v207
	v_mov_b32_e32 v28, v208
	v_mov_b32_e32 v29, v209
	v_mov_b32_e32 v22, v226
	v_mov_b32_e32 v23, v227
	v_mov_b32_e32 v24, v228
	v_mov_b32_e32 v25, v229
	v_mov_b32_e32 v30, v230
	v_mov_b32_e32 v31, v231
	v_mov_b32_e32 v32, v232
	v_mov_b32_e32 v33, v233
	s_waitcnt vmcnt(0)
	v_pk_fma_f32 v[26:27], v[82:83], v[26:27], v[30:31]
	v_pk_add_f32 v[30:31], v[90:91], v[40:41] neg_lo:[0,1] neg_hi:[0,1]
	v_pk_fma_f32 v[26:27], v[46:47], v[44:45], v[26:27] op_sel_hi:[1,0,1]
	v_pk_fma_f32 v[14:15], v[30:31], v[14:15], v[40:41]
	v_pk_add_f32 v[30:31], v[94:95], v[40:41] neg_lo:[0,1] neg_hi:[0,1]
	v_pk_mul_f32 v[26:27], v[26:27], v[96:97]
	v_pk_fma_f32 v[14:15], v[30:31], v[20:21], v[14:15]
	v_pk_mul_f32 v[20:21], v[80:81], v[42:43] op_sel_hi:[1,0]
	s_nop 0
	v_pk_fma_f32 v[20:21], v[20:21], v[28:29], v[32:33]
	s_nop 0
	v_pk_fma_f32 v[14:15], v[14:15], v[44:45], v[20:21] op_sel_hi:[1,0,1]
	s_nop 0
	v_pk_mul_f32 v[14:15], v[14:15], v[2:3]
	v_pk_add_f32 v[2:3], v[88:89], v[38:39] neg_lo:[0,1] neg_hi:[0,1]
	s_nop 0
	v_pk_fma_f32 v[2:3], v[2:3], v[6:7], v[38:39]
	v_pk_add_f32 v[6:7], v[92:93], v[38:39] neg_lo:[0,1] neg_hi:[0,1]
	s_nop 0
	v_pk_fma_f32 v[2:3], v[6:7], v[10:11], v[2:3]
	v_cvt_f32_f16_e32 v6, v4
	v_cvt_f32_f16_sdwa v7, v4 dst_sel:DWORD dst_unused:UNUSED_PAD src0_sel:WORD_1
	v_pk_mul_f32 v[10:11], v[78:79], v[42:43] op_sel_hi:[1,0]
	v_cvt_f32_f16_e32 v4, v5
	v_pk_fma_f32 v[10:11], v[10:11], v[16:17], v[22:23]
	v_cvt_f32_f16_sdwa v5, v5 dst_sel:DWORD dst_unused:UNUSED_PAD src0_sel:WORD_1
	v_pk_fma_f32 v[2:3], v[2:3], v[44:45], v[10:11] op_sel_hi:[1,0,1]
	s_nop 0
	v_pk_mul_f32 v[6:7], v[2:3], v[6:7]
	v_pk_add_f32 v[2:3], v[86:87], v[36:37] neg_lo:[0,1] neg_hi:[0,1]
	s_nop 0
	v_pk_fma_f32 v[2:3], v[2:3], v[8:9], v[36:37]
	v_pk_add_f32 v[8:9], v[84:85], v[36:37] neg_lo:[0,1] neg_hi:[0,1]
	s_nop 0
	v_pk_fma_f32 v[2:3], v[8:9], v[12:13], v[2:3]
	v_pk_mul_f32 v[8:9], v[76:77], v[42:43] op_sel_hi:[1,0]
	s_nop 0
	v_pk_fma_f32 v[8:9], v[8:9], v[18:19], v[24:25]
	s_nop 0
	v_pk_fma_f32 v[2:3], v[2:3], v[44:45], v[8:9] op_sel_hi:[1,0,1]
	s_nop 0
	v_pk_mul_f32 v[8:9], v[2:3], v[4:5]
	v_cvt_pk_f16_f32 v2, v26, v27
	v_cvt_pk_f16_f32 v3, v14, v15
	v_cvt_pk_f16_f32 v4, v6, v7
	v_cvt_pk_f16_f32 v5, v8, v9
	global_store_dwordx4 v[74:75], v[2:5], off
	s_andn2_b64 exec, exec, s[40:41]
	s_cbranch_execz .LBB0_297
.LBB0_285:
	v_mov_b64_e32 v[2:3], s[30:31]
	v_mad_i64_i32 v[26:27], s[38:39], v48, s89, v[2:3]
	v_mov_b32_e32 v71, v34
	v_lshl_add_u64 v[74:75], v[26:27], 0, v[70:71]
	global_load_dwordx4 v[2:5], v[74:75], off
	global_load_dwordx4 v[6:9], v[74:75], off offset:3072
	v_and_b32_e32 v142, 0x7ff, v48
	v_cmp_ne_u32_e32 vcc, 0, v142
	v_mov_b32_e32 v143, 0x1000
	v_mov_b32_e32 v172, 0xfffff100
	v_cndmask_b32_e32 v144, v143, v172, vcc
	v_cndmask_b32_e64 v145, 0, -1, vcc
	s_movk_i32 s100, 0x7ff
	v_lshl_add_u64 v[144:145], v[74:75], 0, v[144:145]
	v_cmp_ne_u32_e32 vcc, s100, v142
	v_mov_b32_e32 v172, 0x2f00
	v_mov_b32_e32 v147, 0
	v_cndmask_b32_e32 v146, v143, v172, vcc
	v_ashrrev_i32_e32 v173, 31, v48
	v_mov_b32_e32 v172, v48
	v_lshl_add_u64 v[146:147], v[74:75], 0, v[146:147]
	v_lshlrev_b64 v[172:173], 10, v[172:173]
	global_load_dwordx4 v[148:151], v[144:145], off
	global_load_dwordx4 v[152:155], v[144:145], off offset:1024
	global_load_dwordx4 v[156:159], v[144:145], off offset:2048
	v_lshl_add_u64 v[172:173], v[56:57], 0, v[172:173]
	global_load_dwordx4 v[160:163], v[146:147], off
	global_load_dwordx4 v[164:167], v[146:147], off offset:1024
	global_load_dwordx4 v[168:171], v[146:147], off offset:2048
	global_load_dwordx4 v[174:177], v[172:173], off
	v_mov_b32_e32 v73, v34
	v_mov_b32_e32 v96, 0
	v_mov_b32_e32 v102, 0
	v_mov_b32_e32 v103, 0
	v_mov_b32_e32 v104, 0
	v_mov_b32_e32 v105, 0
	v_mov_b32_e32 v108, 0
	v_mov_b32_e32 v109, 0
	v_mov_b32_e32 v106, 0
	v_mov_b32_e32 v107, 0
	s_waitcnt vmcnt(8)
	v_cvt_f32_f16_e32 v10, v5
	v_cvt_f32_f16_sdwa v11, v5 dst_sel:DWORD dst_unused:UNUSED_PAD src0_sel:WORD_1
	s_waitcnt vmcnt(7)
	v_cvt_f32_f16_e32 v12, v9
	v_cvt_f32_f16_sdwa v13, v9 dst_sel:DWORD dst_unused:UNUSED_PAD src0_sel:WORD_1
	v_cvt_f32_f16_sdwa v5, v8 dst_sel:DWORD dst_unused:UNUSED_PAD src0_sel:WORD_1
	v_cvt_f32_f16_sdwa v9, v3 dst_sel:DWORD dst_unused:UNUSED_PAD src0_sel:WORD_1
	v_pk_add_f32 v[10:11], v[10:11], v[12:13]
	v_cvt_f32_f16_e32 v12, v4
	v_cvt_f32_f16_sdwa v13, v4 dst_sel:DWORD dst_unused:UNUSED_PAD src0_sel:WORD_1
	v_cvt_f32_f16_e32 v4, v8
	v_cvt_f32_f16_e32 v8, v3
	v_cvt_f32_f16_sdwa v3, v6 dst_sel:DWORD dst_unused:UNUSED_PAD src0_sel:WORD_1
	v_pk_add_f32 v[4:5], v[12:13], v[4:5]
	v_cvt_f32_f16_e32 v12, v7
	v_cvt_f32_f16_sdwa v13, v7 dst_sel:DWORD dst_unused:UNUSED_PAD src0_sel:WORD_1
	v_pk_add_f32 v[8:9], v[8:9], v[12:13]
	v_cvt_f32_f16_e32 v12, v2
	v_cvt_f32_f16_sdwa v13, v2 dst_sel:DWORD dst_unused:UNUSED_PAD src0_sel:WORD_1
	v_cvt_f32_f16_e32 v2, v6
	v_pk_add_f32 v[2:3], v[12:13], v[2:3]
	s_nop 0
	v_add_f32_e32 v6, 0, v2
	v_add_f32_e32 v6, v3, v6
	v_add_f32_e32 v6, v8, v6
	v_add_f32_e32 v6, v9, v6
	v_add_f32_e32 v6, v4, v6
	v_add_f32_e32 v6, v5, v6
	v_add_f32_e32 v6, v10, v6
	v_add_f32_e32 v6, v11, v6
	ds_bpermute_b32 v7, v35, v6
	s_waitcnt lgkmcnt(0)
	v_add_f32_e32 v6, v6, v7
	ds_bpermute_b32 v7, v63, v6
	s_waitcnt lgkmcnt(0)
	v_add_f32_e32 v6, v6, v7
	ds_bpermute_b32 v7, v65, v6
	s_waitcnt lgkmcnt(0)
	v_add_f32_e32 v6, v6, v7
	v_mul_f32_e32 v6, 0x3c800000, v6
	v_pk_add_f32 v[82:83], v[2:3], v[6:7] op_sel_hi:[1,0] neg_lo:[0,1] neg_hi:[0,1]
	v_pk_add_f32 v[80:81], v[8:9], v[6:7] op_sel_hi:[1,0] neg_lo:[0,1] neg_hi:[0,1]
	v_pk_mul_f32 v[2:3], v[82:83], v[82:83]
	v_pk_mul_f32 v[8:9], v[80:81], v[80:81]
	v_add_f32_e32 v2, v2, v3
	v_pk_add_f32 v[78:79], v[4:5], v[6:7] op_sel_hi:[1,0] neg_lo:[0,1] neg_hi:[0,1]
	v_add_f32_e32 v2, v8, v2
	v_pk_mul_f32 v[4:5], v[78:79], v[78:79]
	v_add_f32_e32 v2, v9, v2
	v_pk_add_f32 v[76:77], v[10:11], v[6:7] op_sel_hi:[1,0] neg_lo:[0,1] neg_hi:[0,1]
	v_add_f32_e32 v2, v4, v2
	v_pk_mul_f32 v[6:7], v[76:77], v[76:77]
	v_add_f32_e32 v2, v5, v2
	v_add_f32_e32 v2, v6, v2
	v_add_f32_e32 v2, v7, v2
	ds_bpermute_b32 v3, v35, v2
	v_and_b32_e32 v6, 0x7ff, v48
	v_cmp_ne_u32_e32 vcc, 0, v6
	s_waitcnt lgkmcnt(0)
	v_add_f32_e32 v2, v2, v3
	ds_bpermute_b32 v3, v63, v2
	s_waitcnt lgkmcnt(0)
	v_add_f32_e32 v71, v2, v3
	v_lshl_add_u64 v[2:3], v[26:27], 0, v[72:73]
	global_load_dwordx4 v[2:5], v[2:3], off
	ds_bpermute_b32 v136, v65, v71
	s_and_saveexec_b64 s[38:39], vcc
	s_cbranch_execz .LBB0_287
	s_waitcnt vmcnt(1)
	v_cvt_f32_f16_sdwa v105, v148 dst_sel:DWORD dst_unused:UNUSED_PAD src0_sel:WORD_1
	v_cvt_f32_f16_e32 v104, v148
	v_cvt_f32_f16_sdwa v109, v149 dst_sel:DWORD dst_unused:UNUSED_PAD src0_sel:WORD_1
	v_cvt_f32_f16_e32 v108, v149
	v_cvt_f32_f16_sdwa v107, v150 dst_sel:DWORD dst_unused:UNUSED_PAD src0_sel:WORD_1
	v_cvt_f32_f16_e32 v106, v150
	v_cvt_f32_f16_sdwa v103, v151 dst_sel:DWORD dst_unused:UNUSED_PAD src0_sel:WORD_1
	v_cvt_f32_f16_e32 v102, v151
.LBB0_287:
	s_or_b64 exec, exec, s[38:39]
	s_movk_i32 s33, 0x7ff
	s_mov_b64 s[42:43], 0x1f00
	v_cmp_ne_u32_e64 s[38:39], s33, v6
	v_lshl_add_u64 v[116:117], v[26:27], 0, s[42:43]
	v_mov_b32_e32 v97, 0
	v_mov_b32_e32 v114, 0
	v_mov_b32_e32 v115, 0
	v_mov_b32_e32 v112, 0
	v_mov_b32_e32 v113, 0
	v_mov_b32_e32 v110, 0
	v_mov_b32_e32 v111, 0
	s_and_saveexec_b64 s[42:43], s[38:39]
	s_cbranch_execz .LBB0_289
	v_mov_b32_e32 v73, v34
	v_lshl_add_u64 v[6:7], v[116:117], 0, v[72:73]
	s_waitcnt vmcnt(1)
	v_cvt_f32_f16_e32 v114, v160
	v_cvt_f32_f16_sdwa v115, v160 dst_sel:DWORD dst_unused:UNUSED_PAD src0_sel:WORD_1
	v_cvt_f32_f16_e32 v112, v161
	v_cvt_f32_f16_sdwa v113, v161 dst_sel:DWORD dst_unused:UNUSED_PAD src0_sel:WORD_1
	v_cvt_f32_f16_e32 v110, v162
	v_cvt_f32_f16_sdwa v111, v162 dst_sel:DWORD dst_unused:UNUSED_PAD src0_sel:WORD_1
	v_cvt_f32_f16_e32 v96, v163
	v_cvt_f32_f16_sdwa v97, v163 dst_sel:DWORD dst_unused:UNUSED_PAD src0_sel:WORD_1
.LBB0_289:
	s_or_b64 exec, exec, s[42:43]
	global_load_dwordx4 v[6:9], v[58:59], off offset:16
	global_load_dwordx4 v[18:21], v[58:59], off
	global_load_dwordx4 v[10:13], v[60:61], off offset:16
	global_load_dwordx4 v[14:17], v[60:61], off
	v_lshlrev_b32_e32 v28, 1, v62
	v_mov_b32_e32 v29, v34
	v_lshl_add_u64 v[22:23], v[26:27], 0, v[28:29]
	global_load_dwordx4 v[22:25], v[22:23], off
	v_mov_b32_e32 v118, 0
	v_mov_b32_e32 v120, 0
	v_mov_b32_e32 v121, 0
	v_mov_b32_e32 v126, 0
	v_mov_b32_e32 v127, 0
	v_mov_b32_e32 v124, 0
	v_mov_b32_e32 v125, 0
	v_mov_b32_e32 v122, 0
	v_mov_b32_e32 v123, 0
	s_and_saveexec_b64 s[42:43], vcc
	s_cbranch_execz .LBB0_291
	s_waitcnt vmcnt(6)
	v_cvt_f32_f16_sdwa v127, v152 dst_sel:DWORD dst_unused:UNUSED_PAD src0_sel:WORD_1
	v_cvt_f32_f16_e32 v126, v152
	v_cvt_f32_f16_sdwa v125, v153 dst_sel:DWORD dst_unused:UNUSED_PAD src0_sel:WORD_1
	v_cvt_f32_f16_e32 v124, v153
	v_cvt_f32_f16_sdwa v123, v154 dst_sel:DWORD dst_unused:UNUSED_PAD src0_sel:WORD_1
	v_cvt_f32_f16_e32 v122, v154
	v_cvt_f32_f16_sdwa v121, v155 dst_sel:DWORD dst_unused:UNUSED_PAD src0_sel:WORD_1
	v_cvt_f32_f16_e32 v120, v155
.LBB0_291:
	s_or_b64 exec, exec, s[42:43]
	v_mov_b32_e32 v119, 0
	v_mov_b32_e32 v132, 0
	v_mov_b32_e32 v133, 0
	v_mov_b32_e32 v130, 0
	v_mov_b32_e32 v131, 0
	v_mov_b32_e32 v128, 0
	v_mov_b32_e32 v129, 0
	s_and_saveexec_b64 s[42:43], s[38:39]
	s_cbranch_execz .LBB0_293
	v_mov_b32_e32 v29, v34
	v_lshl_add_u64 v[28:29], v[116:117], 0, v[28:29]
	s_waitcnt vmcnt(6)
	v_cvt_f32_f16_e32 v132, v164
	v_cvt_f32_f16_sdwa v133, v164 dst_sel:DWORD dst_unused:UNUSED_PAD src0_sel:WORD_1
	v_cvt_f32_f16_e32 v130, v165
	v_cvt_f32_f16_sdwa v131, v165 dst_sel:DWORD dst_unused:UNUSED_PAD src0_sel:WORD_1
	v_cvt_f32_f16_e32 v128, v166
	v_cvt_f32_f16_sdwa v129, v166 dst_sel:DWORD dst_unused:UNUSED_PAD src0_sel:WORD_1
	v_cvt_f32_f16_e32 v118, v167
	v_cvt_f32_f16_sdwa v119, v167 dst_sel:DWORD dst_unused:UNUSED_PAD src0_sel:WORD_1
.LBB0_293:
	s_or_b64 exec, exec, s[42:43]
	global_load_dwordx4 v[30:33], v[58:59], off offset:2064
	global_load_dwordx4 v[44:47], v[58:59], off offset:2048
	global_load_dwordx4 v[36:39], v[60:61], off offset:2064
	global_load_dwordx4 v[40:43], v[60:61], off offset:2048
	v_lshlrev_b32_e32 v134, 1, v64
	v_mov_b32_e32 v135, v34
	v_lshl_add_u64 v[26:27], v[26:27], 0, v[134:135]
	global_load_dwordx4 v[26:29], v[26:27], off
	v_mov_b32_e32 v84, 0
	v_mov_b32_e32 v86, 0
	v_mov_b32_e32 v87, 0
	v_mov_b32_e32 v98, 0
	v_mov_b32_e32 v99, 0
	v_mov_b32_e32 v90, 0
	v_mov_b32_e32 v91, 0
	v_mov_b32_e32 v88, 0
	v_mov_b32_e32 v89, 0
	s_and_saveexec_b64 s[42:43], vcc
	s_cbranch_execz .LBB0_295
	s_waitcnt vmcnt(11)
	v_cvt_f32_f16_sdwa v99, v156 dst_sel:DWORD dst_unused:UNUSED_PAD src0_sel:WORD_1
	v_cvt_f32_f16_e32 v98, v156
	v_cvt_f32_f16_sdwa v91, v157 dst_sel:DWORD dst_unused:UNUSED_PAD src0_sel:WORD_1
	v_cvt_f32_f16_e32 v90, v157
	v_cvt_f32_f16_sdwa v89, v158 dst_sel:DWORD dst_unused:UNUSED_PAD src0_sel:WORD_1
	v_cvt_f32_f16_e32 v88, v158
	v_cvt_f32_f16_sdwa v87, v159 dst_sel:DWORD dst_unused:UNUSED_PAD src0_sel:WORD_1
	v_cvt_f32_f16_e32 v86, v159
.LBB0_295:
	s_or_b64 exec, exec, s[42:43]
	v_mov_b32_e32 v85, 0
	v_mov_b32_e32 v100, 0
	v_mov_b32_e32 v101, 0
	v_mov_b32_e32 v94, 0
	v_mov_b32_e32 v95, 0
	v_mov_b32_e32 v92, 0
	v_mov_b32_e32 v93, 0
	s_and_saveexec_b64 s[42:43], s[38:39]
	s_cbranch_execz .LBB0_284
	v_mov_b32_e32 v135, v34
	v_lshl_add_u64 v[84:85], v[116:117], 0, v[134:135]
	s_waitcnt vmcnt(11)
	v_cvt_f32_f16_e32 v100, v168
	v_cvt_f32_f16_sdwa v101, v168 dst_sel:DWORD dst_unused:UNUSED_PAD src0_sel:WORD_1
	v_cvt_f32_f16_e32 v94, v169
	v_cvt_f32_f16_sdwa v95, v169 dst_sel:DWORD dst_unused:UNUSED_PAD src0_sel:WORD_1
	v_cvt_f32_f16_e32 v92, v170
	v_cvt_f32_f16_sdwa v93, v170 dst_sel:DWORD dst_unused:UNUSED_PAD src0_sel:WORD_1
	v_cvt_f32_f16_e32 v84, v171
	v_cvt_f32_f16_sdwa v85, v171 dst_sel:DWORD dst_unused:UNUSED_PAD src0_sel:WORD_1
	s_branch .LBB0_284
